# b15 + UP0/UP1 accumulator reset with 64-bit moves
# speedup vs baseline: 1.0006x; 1.0006x over previous
.LBB0_451:
	s_mov_b32 s62, s50
	s_add_i32 s50, s50, 1
	s_mov_b32 s60, s10
	s_lshr_b32 s10, s50, 3
	s_mul_i32 s10, s10, s51
	s_add_i32 s10, s10, s17
	s_cmpk_lt_i32 s10, 0x58
	s_mov_b32 s61, s12
	s_cselect_b64 s[30:31], -1, 0
	s_lshl_b32 s12, s10, 3
	s_and_b32 s12, s12, 24
	s_add_i32 s12, s12, s72
	s_and_b32 s11, s50, 7
	s_lshl_b32 s12, s12, 3
	s_or_b32 s12, s12, s11
	s_ashr_i32 s13, s12, 31
	s_mov_b64 s[34:35], s[14:15]
	s_ashr_i32 s10, s10, 2
	s_lshl_b64 s[14:15], s[12:13], 19
	s_mov_b64 s[8:9], s[18:19]
	s_add_u32 s18, s64, s14
	s_addc_u32 s19, s65, s15
	s_and_b64 s[14:15], s[30:31], exec
	s_cselect_b32 s63, s19, s9
	s_cselect_b32 s67, s18, s8
	s_ashr_i32 s11, s10, 31
	s_lshl_b64 s[14:15], s[10:11], 19
	s_add_u32 s14, s73, s14
	s_addc_u32 s15, s44, s15
	s_and_b64 s[36:37], s[30:31], exec
	s_cselect_b32 s11, s15, s35
	s_cselect_b32 s68, s14, s34
	s_add_u32 s69, s34, 0x100
	s_addc_u32 s70, s35, 0
	s_mov_b32 s71, -2
	v_mov_b64_e32 v[56:57], 0
	v_mov_b64_e32 v[58:59], 0
	v_mov_b64_e32 v[52:53], 0
	v_mov_b64_e32 v[54:55], 0
	v_mov_b64_e32 v[48:49], 0
	v_mov_b64_e32 v[50:51], 0
	v_mov_b64_e32 v[44:45], 0
	v_mov_b64_e32 v[46:47], 0
	v_mov_b64_e32 v[0:1], 0
	v_mov_b64_e32 v[2:3], 0
	v_mov_b64_e32 v[60:61], 0
	v_mov_b64_e32 v[62:63], 0
	v_mov_b64_e32 v[4:5], 0
	v_mov_b64_e32 v[6:7], 0
	v_mov_b64_e32 v[64:65], 0
	v_mov_b64_e32 v[66:67], 0
	v_mov_b64_e32 v[116:117], 0
	v_mov_b64_e32 v[118:119], 0
	v_mov_b64_e32 v[120:121], 0
	v_mov_b64_e32 v[122:123], 0
	v_mov_b64_e32 v[124:125], 0
	v_mov_b64_e32 v[126:127], 0
	v_mov_b64_e32 v[128:129], 0
	v_mov_b64_e32 v[130:131], 0
	v_mov_b64_e32 v[8:9], 0
	v_mov_b64_e32 v[10:11], 0
	v_mov_b64_e32 v[72:73], 0
	v_mov_b64_e32 v[74:75], 0
	v_mov_b64_e32 v[12:13], 0
	v_mov_b64_e32 v[14:15], 0
	v_mov_b64_e32 v[76:77], 0
	v_mov_b64_e32 v[78:79], 0
	v_mov_b64_e32 v[88:89], 0
	v_mov_b64_e32 v[90:91], 0
	v_mov_b64_e32 v[84:85], 0
	v_mov_b64_e32 v[86:87], 0
	v_mov_b64_e32 v[92:93], 0
	v_mov_b64_e32 v[94:95], 0
	v_mov_b64_e32 v[80:81], 0
	v_mov_b64_e32 v[82:83], 0
	v_mov_b64_e32 v[28:29], 0
	v_mov_b64_e32 v[30:31], 0
	v_mov_b64_e32 v[100:101], 0
	v_mov_b64_e32 v[102:103], 0
	v_mov_b64_e32 v[32:33], 0
	v_mov_b64_e32 v[34:35], 0
	v_mov_b64_e32 v[104:105], 0
	v_mov_b64_e32 v[106:107], 0
	v_mov_b64_e32 v[132:133], 0
	v_mov_b64_e32 v[134:135], 0
	v_mov_b64_e32 v[136:137], 0
	v_mov_b64_e32 v[138:139], 0
	v_mov_b64_e32 v[140:141], 0
	v_mov_b64_e32 v[142:143], 0
	v_mov_b64_e32 v[144:145], 0
	v_mov_b64_e32 v[146:147], 0
	v_mov_b64_e32 v[36:37], 0
	v_mov_b64_e32 v[38:39], 0
	v_mov_b64_e32 v[108:109], 0
	v_mov_b64_e32 v[110:111], 0
	v_mov_b64_e32 v[40:41], 0
	v_mov_b64_e32 v[42:43], 0
	v_mov_b64_e32 v[112:113], 0
	v_mov_b64_e32 v[114:115], 0

.LBB0_1638:
	s_mov_b32 s58, s46
	s_add_i32 s46, s46, 1
	s_mov_b32 s56, s10
	s_lshr_b32 s10, s46, 3
	s_mul_i32 s10, s10, s47
	s_add_i32 s10, s10, s37
	s_cmpk_lt_i32 s10, 0x58
	s_mov_b32 s57, s12
	s_cselect_b64 s[26:27], -1, 0
	s_lshl_b32 s12, s10, 3
	s_and_b32 s12, s12, 24
	s_add_i32 s12, s12, s38
	s_and_b32 s11, s46, 7
	s_lshl_b32 s12, s12, 3
	s_or_b32 s12, s12, s11
	s_ashr_i32 s13, s12, 31
	s_mov_b64 s[28:29], s[14:15]
	s_ashr_i32 s10, s10, 2
	s_lshl_b64 s[14:15], s[12:13], 19
	s_mov_b64 s[8:9], s[16:17]
	s_add_u32 s16, s64, s14
	s_addc_u32 s17, s65, s15
	s_and_b64 s[14:15], s[26:27], exec
	s_cselect_b32 s59, s17, s9
	s_cselect_b32 s60, s16, s8
	s_ashr_i32 s11, s10, 31
	s_lshl_b64 s[14:15], s[10:11], 19
	s_add_u32 s14, s39, s14
	s_addc_u32 s15, s40, s15
	s_and_b64 s[30:31], s[26:27], exec
	s_cselect_b32 s11, s15, s29
	s_cselect_b32 s61, s14, s28
	s_add_u32 s62, s28, 0x100
	s_addc_u32 s63, s29, 0
	s_mov_b32 s67, -2
	v_mov_b64_e32 v[56:57], 0
	v_mov_b64_e32 v[58:59], 0
	v_mov_b64_e32 v[52:53], 0
	v_mov_b64_e32 v[54:55], 0
	v_mov_b64_e32 v[48:49], 0
	v_mov_b64_e32 v[50:51], 0
	v_mov_b64_e32 v[44:45], 0
	v_mov_b64_e32 v[46:47], 0
	v_mov_b64_e32 v[0:1], 0
	v_mov_b64_e32 v[2:3], 0
	v_mov_b64_e32 v[60:61], 0
	v_mov_b64_e32 v[62:63], 0
	v_mov_b64_e32 v[4:5], 0
	v_mov_b64_e32 v[6:7], 0
	v_mov_b64_e32 v[64:65], 0
	v_mov_b64_e32 v[66:67], 0
	v_mov_b64_e32 v[116:117], 0
	v_mov_b64_e32 v[118:119], 0
	v_mov_b64_e32 v[120:121], 0
	v_mov_b64_e32 v[122:123], 0
	v_mov_b64_e32 v[124:125], 0
	v_mov_b64_e32 v[126:127], 0
	v_mov_b64_e32 v[128:129], 0
	v_mov_b64_e32 v[130:131], 0
	v_mov_b64_e32 v[8:9], 0
	v_mov_b64_e32 v[10:11], 0
	v_mov_b64_e32 v[72:73], 0
	v_mov_b64_e32 v[74:75], 0
	v_mov_b64_e32 v[12:13], 0
	v_mov_b64_e32 v[14:15], 0
	v_mov_b64_e32 v[76:77], 0
	v_mov_b64_e32 v[78:79], 0
	v_mov_b64_e32 v[88:89], 0
	v_mov_b64_e32 v[90:91], 0
	v_mov_b64_e32 v[84:85], 0
	v_mov_b64_e32 v[86:87], 0
	v_mov_b64_e32 v[92:93], 0
	v_mov_b64_e32 v[94:95], 0
	v_mov_b64_e32 v[80:81], 0
	v_mov_b64_e32 v[82:83], 0
	v_mov_b64_e32 v[28:29], 0
	v_mov_b64_e32 v[30:31], 0
	v_mov_b64_e32 v[100:101], 0
	v_mov_b64_e32 v[102:103], 0
	v_mov_b64_e32 v[32:33], 0
	v_mov_b64_e32 v[34:35], 0
	v_mov_b64_e32 v[104:105], 0
	v_mov_b64_e32 v[106:107], 0
	v_mov_b64_e32 v[132:133], 0
	v_mov_b64_e32 v[134:135], 0
	v_mov_b64_e32 v[136:137], 0
	v_mov_b64_e32 v[138:139], 0
	v_mov_b64_e32 v[140:141], 0
	v_mov_b64_e32 v[142:143], 0
	v_mov_b64_e32 v[144:145], 0
	v_mov_b64_e32 v[146:147], 0
	v_mov_b64_e32 v[36:37], 0
	v_mov_b64_e32 v[38:39], 0
	v_mov_b64_e32 v[108:109], 0
	v_mov_b64_e32 v[110:111], 0
	v_mov_b64_e32 v[40:41], 0
	v_mov_b64_e32 v[42:43], 0
	v_mov_b64_e32 v[112:113], 0
	v_mov_b64_e32 v[114:115], 0
